# indexer sweeps: every packed-VALU block and MFMA pair of the score core aligned to 8 bytes (.p2align 3), later code kept at the same offsets
# baseline (speedup 1.0000x reference)
;     ...
;     for (int it = 0; it < nit; ++it) {
;         const int kt = kt0 + 4 * (it >> 1), kb = it & 1;
;         const int itn = it + 1 < nit ? it + 1 : it;
;         const bf16_t* np = ikp + (size_t)(256 * (itn >> 1) + 32 * (itn & 1)) * NZ; const bf16x8 n0 = *(const bf16x8*)np, n1 = *(const bf16x8*)(np + 16);
;         f32x2v sc2[8];
; #pragma unroll
;         for (int r = 0; r < 8; ++r) sc2[r] = (f32x2v){0.f, 0.f};
;     ...
;         { f32x16 zero16;
; #pragma unroll
;           for (int r = 0; r < 16; ++r) zero16[r] = 0.f;
;           f32x16 dA0, dA1, dB0, dB1; float wA0, wA1, wB0, wB1;
;           SW_MF(0, dA0, dA1, wA0, wA1);
;           SW_MF(1, dB0, dB1, wB0, wB1); __builtin_amdgcn_sched_barrier(0);
;           SW_VA(dA0, dA1, wA0, wA1);    __builtin_amdgcn_sched_barrier(0);
;           SW_MF(2, dA0, dA1, wA0, wA1); __builtin_amdgcn_sched_barrier(0);
;           SW_VA(dB0, dB1, wB0, wB1);    __builtin_amdgcn_sched_barrier(0);
;           SW_MF(3, dB0, dB1, wB0, wB1); __builtin_amdgcn_sched_barrier(0);
;           SW_VA(dA0, dA1, wA0, wA1);    __builtin_amdgcn_sched_barrier(0);
;           SW_VA(dB0, dB1, wB0, wB1); }
.Lstag_m5:
.Lm5_loop:
	.p2align 3
	v_mfma_f32_32x32x16_bf16 v[16:31], v[76:79], v[0:3], 0
	v_mfma_f32_32x32x16_bf16 v[16:31], v[72:75], v[4:7], v[16:31]
	ds_read_b128 v[0:3], v165 offset:128
	ds_read_b128 v[4:7], v165 offset:160
	.p2align 3
	v_mfma_f32_32x32x16_bf16 v[32:47], v[76:79], v[8:11], 0
	v_mfma_f32_32x32x16_bf16 v[32:47], v[72:75], v[12:15], v[32:47]
	ds_read_b128 v[8:11], v165 offset:192
	ds_read_b128 v[12:15], v165 offset:224
	s_add_i32 s1, s2, 1
	s_cmp_lt_u32 s1, s25
	s_cselect_b32 s3, s1, s2
	s_lshl_b32 vcc_lo, s3, 7
	s_and_b32 vcc_lo, vcc_lo, 0x7fffff00
	s_lshl_b32 s3, s3, 5
	s_and_b32 s3, s3, 32
	s_or_b32 s3, vcc_lo, s3
	v_mad_u64_u32 v[114:115], vcc, s3, v223, v[140:141]
	global_load_dwordx4 v[64:67], v[114:115], off
	global_load_dwordx4 v[68:71], v[114:115], off offset:32
	.p2align 3
	v_pk_mul_f32 v[16:17], v[16:17], v[112:113] clamp
	v_pk_mul_f32 v[18:19], v[18:19], v[112:113] clamp
	v_pk_mul_f32 v[20:21], v[20:21], v[112:113] clamp
	v_pk_mul_f32 v[22:23], v[22:23], v[112:113] clamp
	v_pk_mul_f32 v[24:25], v[24:25], v[112:113] clamp
	v_pk_mul_f32 v[26:27], v[26:27], v[112:113] clamp
	v_pk_mul_f32 v[28:29], v[28:29], v[112:113] clamp
	v_pk_mul_f32 v[30:31], v[30:31], v[112:113] clamp
	v_pk_fma_f32 v[88:89], v[16:17], v[80:81], 0 op_sel_hi:[1,0,0]
	v_pk_fma_f32 v[90:91], v[18:19], v[80:81], 0 op_sel_hi:[1,0,0]
	v_pk_fma_f32 v[92:93], v[20:21], v[80:81], 0 op_sel_hi:[1,0,0]
	v_pk_fma_f32 v[94:95], v[22:23], v[80:81], 0 op_sel_hi:[1,0,0]
	v_pk_fma_f32 v[96:97], v[24:25], v[80:81], 0 op_sel_hi:[1,0,0]
	v_pk_fma_f32 v[98:99], v[26:27], v[80:81], 0 op_sel_hi:[1,0,0]
	v_pk_fma_f32 v[100:101], v[28:29], v[80:81], 0 op_sel_hi:[1,0,0]
	v_pk_fma_f32 v[102:103], v[30:31], v[80:81], 0 op_sel_hi:[1,0,0]
	s_waitcnt lgkmcnt(2)
	.p2align 3
	v_mfma_f32_32x32x16_bf16 v[16:31], v[76:79], v[0:3], 0
	v_mfma_f32_32x32x16_bf16 v[16:31], v[72:75], v[4:7], v[16:31]
	ds_read_b128 v[0:3], v165 offset:256
	ds_read_b128 v[4:7], v165 offset:288
	.p2align 3
	v_pk_mul_f32 v[32:33], v[32:33], v[112:113] clamp
	v_pk_mul_f32 v[34:35], v[34:35], v[112:113] clamp
	v_pk_mul_f32 v[36:37], v[36:37], v[112:113] clamp
	v_pk_mul_f32 v[38:39], v[38:39], v[112:113] clamp
	v_pk_mul_f32 v[40:41], v[40:41], v[112:113] clamp
	v_pk_mul_f32 v[42:43], v[42:43], v[112:113] clamp
	v_pk_mul_f32 v[44:45], v[44:45], v[112:113] clamp
	v_pk_mul_f32 v[46:47], v[46:47], v[112:113] clamp
	v_pk_fma_f32 v[88:89], v[32:33], v[104:105], v[88:89] op_sel_hi:[1,0,1]
	v_pk_fma_f32 v[90:91], v[34:35], v[104:105], v[90:91] op_sel_hi:[1,0,1]
	v_pk_fma_f32 v[92:93], v[36:37], v[104:105], v[92:93] op_sel_hi:[1,0,1]
	v_pk_fma_f32 v[94:95], v[38:39], v[104:105], v[94:95] op_sel_hi:[1,0,1]
	v_pk_fma_f32 v[96:97], v[40:41], v[104:105], v[96:97] op_sel_hi:[1,0,1]
	v_pk_fma_f32 v[98:99], v[42:43], v[104:105], v[98:99] op_sel_hi:[1,0,1]
	v_pk_fma_f32 v[100:101], v[44:45], v[104:105], v[100:101] op_sel_hi:[1,0,1]
	v_pk_fma_f32 v[102:103], v[46:47], v[104:105], v[102:103] op_sel_hi:[1,0,1]
	s_waitcnt lgkmcnt(2)
	.p2align 3
	v_mfma_f32_32x32x16_bf16 v[32:47], v[76:79], v[8:11], 0
	v_mfma_f32_32x32x16_bf16 v[32:47], v[72:75], v[12:15], v[32:47]
	ds_read_b128 v[8:11], v165 offset:320
	ds_read_b128 v[12:15], v165 offset:352
	.p2align 3
	v_pk_mul_f32 v[16:17], v[16:17], v[112:113] clamp
	v_pk_mul_f32 v[18:19], v[18:19], v[112:113] clamp
	v_pk_mul_f32 v[20:21], v[20:21], v[112:113] clamp
	v_pk_mul_f32 v[22:23], v[22:23], v[112:113] clamp
	v_pk_mul_f32 v[24:25], v[24:25], v[112:113] clamp
	v_pk_mul_f32 v[26:27], v[26:27], v[112:113] clamp
	v_pk_mul_f32 v[28:29], v[28:29], v[112:113] clamp
	v_pk_mul_f32 v[30:31], v[30:31], v[112:113] clamp
	v_pk_fma_f32 v[88:89], v[16:17], v[82:83], v[88:89] op_sel_hi:[1,0,1]
	v_pk_fma_f32 v[90:91], v[18:19], v[82:83], v[90:91] op_sel_hi:[1,0,1]
	v_pk_fma_f32 v[92:93], v[20:21], v[82:83], v[92:93] op_sel_hi:[1,0,1]
	v_pk_fma_f32 v[94:95], v[22:23], v[82:83], v[94:95] op_sel_hi:[1,0,1]
	v_pk_fma_f32 v[96:97], v[24:25], v[82:83], v[96:97] op_sel_hi:[1,0,1]
	v_pk_fma_f32 v[98:99], v[26:27], v[82:83], v[98:99] op_sel_hi:[1,0,1]
	v_pk_fma_f32 v[100:101], v[28:29], v[82:83], v[100:101] op_sel_hi:[1,0,1]
	v_pk_fma_f32 v[102:103], v[30:31], v[82:83], v[102:103] op_sel_hi:[1,0,1]
	s_waitcnt lgkmcnt(2)
	.p2align 3
	v_mfma_f32_32x32x16_bf16 v[16:31], v[76:79], v[0:3], 0
	v_mfma_f32_32x32x16_bf16 v[16:31], v[72:75], v[4:7], v[16:31]
	ds_read_b128 v[0:3], v165 offset:384
	ds_read_b128 v[4:7], v165 offset:416
	.p2align 3
	v_pk_mul_f32 v[32:33], v[32:33], v[112:113] clamp
	v_pk_mul_f32 v[34:35], v[34:35], v[112:113] clamp
	v_pk_mul_f32 v[36:37], v[36:37], v[112:113] clamp
	v_pk_mul_f32 v[38:39], v[38:39], v[112:113] clamp
	v_pk_mul_f32 v[40:41], v[40:41], v[112:113] clamp
	v_pk_mul_f32 v[42:43], v[42:43], v[112:113] clamp
	v_pk_mul_f32 v[44:45], v[44:45], v[112:113] clamp
	v_pk_mul_f32 v[46:47], v[46:47], v[112:113] clamp
	v_pk_fma_f32 v[88:89], v[32:33], v[106:107], v[88:89] op_sel_hi:[1,0,1]
	v_pk_fma_f32 v[90:91], v[34:35], v[106:107], v[90:91] op_sel_hi:[1,0,1]
	v_pk_fma_f32 v[92:93], v[36:37], v[106:107], v[92:93] op_sel_hi:[1,0,1]
	v_pk_fma_f32 v[94:95], v[38:39], v[106:107], v[94:95] op_sel_hi:[1,0,1]
	v_pk_fma_f32 v[96:97], v[40:41], v[106:107], v[96:97] op_sel_hi:[1,0,1]
	v_pk_fma_f32 v[98:99], v[42:43], v[106:107], v[98:99] op_sel_hi:[1,0,1]
	v_pk_fma_f32 v[100:101], v[44:45], v[106:107], v[100:101] op_sel_hi:[1,0,1]
	v_pk_fma_f32 v[102:103], v[46:47], v[106:107], v[102:103] op_sel_hi:[1,0,1]
	s_waitcnt lgkmcnt(2)
;     ...
;         { f32x16 zero16;
; #pragma unroll
;           for (int r = 0; r < 16; ++r) zero16[r] = 0.f;
;           f32x16 dA0, dA1, dB0, dB1; float wA0, wA1, wB0, wB1;
;           SW_MF(0, dA0, dA1, wA0, wA1);
;           SW_MF(1, dB0, dB1, wB0, wB1); __builtin_amdgcn_sched_barrier(0);
;           SW_VA(dA0, dA1, wA0, wA1);    __builtin_amdgcn_sched_barrier(0);
;           SW_MF(2, dA0, dA1, wA0, wA1); __builtin_amdgcn_sched_barrier(0);
;           SW_VA(dB0, dB1, wB0, wB1);    __builtin_amdgcn_sched_barrier(0);
;           SW_MF(3, dB0, dB1, wB0, wB1); __builtin_amdgcn_sched_barrier(0);
;           SW_VA(dA0, dA1, wA0, wA1);    __builtin_amdgcn_sched_barrier(0);
;           SW_VA(dB0, dB1, wB0, wB1); }
	.p2align 3
	v_mfma_f32_32x32x16_bf16 v[32:47], v[76:79], v[8:11], 0
	v_mfma_f32_32x32x16_bf16 v[32:47], v[72:75], v[12:15], v[32:47]
	ds_read_b128 v[8:11], v165 offset:448
	ds_read_b128 v[12:15], v165 offset:480
	.p2align 3
	v_pk_mul_f32 v[16:17], v[16:17], v[112:113] clamp
	v_pk_mul_f32 v[18:19], v[18:19], v[112:113] clamp
	v_pk_mul_f32 v[20:21], v[20:21], v[112:113] clamp
	v_pk_mul_f32 v[22:23], v[22:23], v[112:113] clamp
	v_pk_mul_f32 v[24:25], v[24:25], v[112:113] clamp
	v_pk_mul_f32 v[26:27], v[26:27], v[112:113] clamp
	v_pk_mul_f32 v[28:29], v[28:29], v[112:113] clamp
	v_pk_mul_f32 v[30:31], v[30:31], v[112:113] clamp
	v_pk_fma_f32 v[88:89], v[16:17], v[84:85], v[88:89] op_sel_hi:[1,0,1]
	v_pk_fma_f32 v[90:91], v[18:19], v[84:85], v[90:91] op_sel_hi:[1,0,1]
	v_pk_fma_f32 v[92:93], v[20:21], v[84:85], v[92:93] op_sel_hi:[1,0,1]
	v_pk_fma_f32 v[94:95], v[22:23], v[84:85], v[94:95] op_sel_hi:[1,0,1]
	v_pk_fma_f32 v[96:97], v[24:25], v[84:85], v[96:97] op_sel_hi:[1,0,1]
	v_pk_fma_f32 v[98:99], v[26:27], v[84:85], v[98:99] op_sel_hi:[1,0,1]
	v_pk_fma_f32 v[100:101], v[28:29], v[84:85], v[100:101] op_sel_hi:[1,0,1]
	v_pk_fma_f32 v[102:103], v[30:31], v[84:85], v[102:103] op_sel_hi:[1,0,1]
	s_waitcnt lgkmcnt(2)
	.p2align 3
	v_mfma_f32_32x32x16_bf16 v[16:31], v[76:79], v[0:3], 0
	v_mfma_f32_32x32x16_bf16 v[16:31], v[72:75], v[4:7], v[16:31]
	ds_read_b128 v[0:3], v165
	ds_read_b128 v[4:7], v165 offset:32
	.p2align 3
	v_pk_mul_f32 v[32:33], v[32:33], v[112:113] clamp
	v_pk_mul_f32 v[34:35], v[34:35], v[112:113] clamp
	v_pk_mul_f32 v[36:37], v[36:37], v[112:113] clamp
	v_pk_mul_f32 v[38:39], v[38:39], v[112:113] clamp
	v_pk_mul_f32 v[40:41], v[40:41], v[112:113] clamp
	v_pk_mul_f32 v[42:43], v[42:43], v[112:113] clamp
	v_pk_mul_f32 v[44:45], v[44:45], v[112:113] clamp
	v_pk_mul_f32 v[46:47], v[46:47], v[112:113] clamp
	v_pk_fma_f32 v[88:89], v[32:33], v[108:109], v[88:89] op_sel_hi:[1,0,1]
	v_pk_fma_f32 v[90:91], v[34:35], v[108:109], v[90:91] op_sel_hi:[1,0,1]
	v_pk_fma_f32 v[92:93], v[36:37], v[108:109], v[92:93] op_sel_hi:[1,0,1]
	v_pk_fma_f32 v[94:95], v[38:39], v[108:109], v[94:95] op_sel_hi:[1,0,1]
	v_pk_fma_f32 v[96:97], v[40:41], v[108:109], v[96:97] op_sel_hi:[1,0,1]
	v_pk_fma_f32 v[98:99], v[42:43], v[108:109], v[98:99] op_sel_hi:[1,0,1]
	v_pk_fma_f32 v[100:101], v[44:45], v[108:109], v[100:101] op_sel_hi:[1,0,1]
	v_pk_fma_f32 v[102:103], v[46:47], v[108:109], v[102:103] op_sel_hi:[1,0,1]
	s_waitcnt lgkmcnt(2)
	.p2align 3
	v_mfma_f32_32x32x16_bf16 v[32:47], v[76:79], v[8:11], 0
	v_mfma_f32_32x32x16_bf16 v[32:47], v[72:75], v[12:15], v[32:47]
	ds_read_b128 v[8:11], v165 offset:64
	ds_read_b128 v[12:15], v165 offset:96
	.p2align 3
	v_pk_mul_f32 v[16:17], v[16:17], v[112:113] clamp
	v_pk_mul_f32 v[18:19], v[18:19], v[112:113] clamp
	v_pk_mul_f32 v[20:21], v[20:21], v[112:113] clamp
	v_pk_mul_f32 v[22:23], v[22:23], v[112:113] clamp
	v_pk_mul_f32 v[24:25], v[24:25], v[112:113] clamp
	v_pk_mul_f32 v[26:27], v[26:27], v[112:113] clamp
	v_pk_mul_f32 v[28:29], v[28:29], v[112:113] clamp
	v_pk_mul_f32 v[30:31], v[30:31], v[112:113] clamp
	v_pk_fma_f32 v[88:89], v[16:17], v[86:87], v[88:89] op_sel_hi:[1,0,1]
	v_pk_fma_f32 v[90:91], v[18:19], v[86:87], v[90:91] op_sel_hi:[1,0,1]
	v_pk_fma_f32 v[92:93], v[20:21], v[86:87], v[92:93] op_sel_hi:[1,0,1]
	v_pk_fma_f32 v[94:95], v[22:23], v[86:87], v[94:95] op_sel_hi:[1,0,1]
	v_pk_fma_f32 v[96:97], v[24:25], v[86:87], v[96:97] op_sel_hi:[1,0,1]
	v_pk_fma_f32 v[98:99], v[26:27], v[86:87], v[98:99] op_sel_hi:[1,0,1]
	v_pk_fma_f32 v[100:101], v[28:29], v[86:87], v[100:101] op_sel_hi:[1,0,1]
	v_pk_fma_f32 v[102:103], v[30:31], v[86:87], v[102:103] op_sel_hi:[1,0,1]
	.p2align 3
	v_pk_mul_f32 v[32:33], v[32:33], v[112:113] clamp
	v_pk_mul_f32 v[34:35], v[34:35], v[112:113] clamp
	v_pk_mul_f32 v[36:37], v[36:37], v[112:113] clamp
	v_pk_mul_f32 v[38:39], v[38:39], v[112:113] clamp
	v_pk_mul_f32 v[40:41], v[40:41], v[112:113] clamp
	v_pk_mul_f32 v[42:43], v[42:43], v[112:113] clamp
	v_pk_mul_f32 v[44:45], v[44:45], v[112:113] clamp
	v_pk_mul_f32 v[46:47], v[46:47], v[112:113] clamp
	v_pk_fma_f32 v[88:89], v[32:33], v[110:111], v[88:89] op_sel_hi:[1,0,1]
	v_pk_fma_f32 v[90:91], v[34:35], v[110:111], v[90:91] op_sel_hi:[1,0,1]
	v_pk_fma_f32 v[92:93], v[36:37], v[110:111], v[92:93] op_sel_hi:[1,0,1]
	v_pk_fma_f32 v[94:95], v[38:39], v[110:111], v[94:95] op_sel_hi:[1,0,1]
	v_pk_fma_f32 v[96:97], v[40:41], v[110:111], v[96:97] op_sel_hi:[1,0,1]
	v_pk_fma_f32 v[98:99], v[42:43], v[110:111], v[98:99] op_sel_hi:[1,0,1]
	v_pk_fma_f32 v[100:101], v[44:45], v[110:111], v[100:101] op_sel_hi:[1,0,1]
	v_pk_fma_f32 v[102:103], v[46:47], v[110:111], v[102:103] op_sel_hi:[1,0,1]
	s_waitcnt lgkmcnt(0)
; __device__ __forceinline__ int bucketf(float f) { const unsigned u = __float_as_uint(f); const int idx = (int)((u >> 20) & 0x7FFu); const int c = min(max(idx - 816, 128), 255); return c ^ (((int)u >> 31) & 255); }
;     ...
;         const unsigned s0 = (unsigned)(64 * kt + 32 * kb + 4 * hi);
; #pragma unroll
;         for (int r = 0; r < 16; ++r) { const unsigned s = s0 + (unsigned)((r & 3) + 8 * (r >> 2));
;             if (MODE == 5) { __hip_atomic_fetch_add(hist + 64 * bucketf(sc[r]), 1u, __ATOMIC_RELAXED, __HIP_MEMORY_SCOPE_WORKGROUP); continue; }
;     ...
;         a0 = n0; a1 = n1;
;     }
	v_bfe_u32 v48, v88, 20, 11
	v_ashrrev_i32_e32 v49, 31, v88
	v_med3_u32 v48, v48, v117, v118
	v_bitop3_b32 v48, v48, v49, s56 bitop3:0x78
	v_lshl_add_u32 v48, v48, 8, v116
	ds_add_u32 v48, v222
	v_bfe_u32 v50, v89, 20, 11
	v_ashrrev_i32_e32 v51, 31, v89
	v_med3_u32 v50, v50, v117, v118
	v_bitop3_b32 v50, v50, v51, s56 bitop3:0x78
	v_lshl_add_u32 v50, v50, 8, v116
	ds_add_u32 v50, v222
	v_bfe_u32 v52, v90, 20, 11
	v_ashrrev_i32_e32 v53, 31, v90
	v_med3_u32 v52, v52, v117, v118
	v_bitop3_b32 v52, v52, v53, s56 bitop3:0x78
	v_lshl_add_u32 v52, v52, 8, v116
	ds_add_u32 v52, v222
	v_bfe_u32 v54, v91, 20, 11
	v_ashrrev_i32_e32 v55, 31, v91
	v_med3_u32 v54, v54, v117, v118
	v_bitop3_b32 v54, v54, v55, s56 bitop3:0x78
	v_lshl_add_u32 v54, v54, 8, v116
	ds_add_u32 v54, v222
	v_bfe_u32 v48, v92, 20, 11
	v_ashrrev_i32_e32 v49, 31, v92
	v_med3_u32 v48, v48, v117, v118
	v_bitop3_b32 v48, v48, v49, s56 bitop3:0x78
	v_lshl_add_u32 v48, v48, 8, v116
	ds_add_u32 v48, v222
	v_bfe_u32 v50, v93, 20, 11
	v_ashrrev_i32_e32 v51, 31, v93
	v_med3_u32 v50, v50, v117, v118
	v_bitop3_b32 v50, v50, v51, s56 bitop3:0x78
	v_lshl_add_u32 v50, v50, 8, v116
	ds_add_u32 v50, v222
	v_bfe_u32 v52, v94, 20, 11
	v_ashrrev_i32_e32 v53, 31, v94
	v_med3_u32 v52, v52, v117, v118
	v_bitop3_b32 v52, v52, v53, s56 bitop3:0x78
	v_lshl_add_u32 v52, v52, 8, v116
	ds_add_u32 v52, v222
	v_bfe_u32 v54, v95, 20, 11
	v_ashrrev_i32_e32 v55, 31, v95
	v_med3_u32 v54, v54, v117, v118
	v_bitop3_b32 v54, v54, v55, s56 bitop3:0x78
	v_lshl_add_u32 v54, v54, 8, v116
	ds_add_u32 v54, v222
	v_bfe_u32 v48, v96, 20, 11
	v_ashrrev_i32_e32 v49, 31, v96
	v_med3_u32 v48, v48, v117, v118
	v_bitop3_b32 v48, v48, v49, s56 bitop3:0x78
	v_lshl_add_u32 v48, v48, 8, v116
	ds_add_u32 v48, v222
	v_bfe_u32 v50, v97, 20, 11
	v_ashrrev_i32_e32 v51, 31, v97
	v_med3_u32 v50, v50, v117, v118
	v_bitop3_b32 v50, v50, v51, s56 bitop3:0x78
	v_lshl_add_u32 v50, v50, 8, v116
	ds_add_u32 v50, v222
	v_bfe_u32 v52, v98, 20, 11
	v_ashrrev_i32_e32 v53, 31, v98
	v_med3_u32 v52, v52, v117, v118
	v_bitop3_b32 v52, v52, v53, s56 bitop3:0x78
	v_lshl_add_u32 v52, v52, 8, v116
	ds_add_u32 v52, v222
	v_bfe_u32 v54, v99, 20, 11
	v_ashrrev_i32_e32 v55, 31, v99
	v_med3_u32 v54, v54, v117, v118
	v_bitop3_b32 v54, v54, v55, s56 bitop3:0x78
	v_lshl_add_u32 v54, v54, 8, v116
	ds_add_u32 v54, v222
	v_bfe_u32 v48, v100, 20, 11
	v_ashrrev_i32_e32 v49, 31, v100
	v_med3_u32 v48, v48, v117, v118
	v_bitop3_b32 v48, v48, v49, s56 bitop3:0x78
	v_lshl_add_u32 v48, v48, 8, v116
	ds_add_u32 v48, v222
	v_bfe_u32 v50, v101, 20, 11
	v_ashrrev_i32_e32 v51, 31, v101
	v_med3_u32 v50, v50, v117, v118
	v_bitop3_b32 v50, v50, v51, s56 bitop3:0x78
	v_lshl_add_u32 v50, v50, 8, v116
	ds_add_u32 v50, v222
	v_bfe_u32 v52, v102, 20, 11
	v_ashrrev_i32_e32 v53, 31, v102
	v_med3_u32 v52, v52, v117, v118
	v_bitop3_b32 v52, v52, v53, s56 bitop3:0x78
	v_lshl_add_u32 v52, v52, 8, v116
	ds_add_u32 v52, v222
	v_bfe_u32 v54, v103, 20, 11
	v_ashrrev_i32_e32 v55, 31, v103
	v_med3_u32 v54, v54, v117, v118
	v_bitop3_b32 v54, v54, v55, s56 bitop3:0x78
	v_lshl_add_u32 v54, v54, 8, v116
	ds_add_u32 v54, v222
	s_waitcnt vmcnt(0)
	v_mov_b64_e32 v[76:77], v[64:65]
	v_mov_b64_e32 v[78:79], v[66:67]
	v_mov_b64_e32 v[72:73], v[68:69]
	v_mov_b64_e32 v[74:75], v[70:71]
	s_cmp_lg_u32 s25, s1
	s_mov_b32 s2, s1
	s_cbranch_scc1 .Lm5_loop

;     ...
;     for (int it = 0; it < nit; ++it) {
;         const int kt = kt0 + 4 * (it >> 1), kb = it & 1;
;         const int itn = it + 1 < nit ? it + 1 : it;
;         const bf16_t* np = ikp + (size_t)(256 * (itn >> 1) + 32 * (itn & 1)) * NZ; const bf16x8 n0 = *(const bf16x8*)np, n1 = *(const bf16x8*)(np + 16);
;         f32x2v sc2[8];
; #pragma unroll
;         for (int r = 0; r < 8; ++r) sc2[r] = (f32x2v){0.f, 0.f};
;     ...
;         { f32x16 zero16;
; #pragma unroll
;           for (int r = 0; r < 16; ++r) zero16[r] = 0.f;
;           f32x16 dA0, dA1, dB0, dB1; float wA0, wA1, wB0, wB1;
;           SW_MF(0, dA0, dA1, wA0, wA1);
;           SW_MF(1, dB0, dB1, wB0, wB1); __builtin_amdgcn_sched_barrier(0);
;           SW_VA(dA0, dA1, wA0, wA1);    __builtin_amdgcn_sched_barrier(0);
;           SW_MF(2, dA0, dA1, wA0, wA1); __builtin_amdgcn_sched_barrier(0);
;           SW_VA(dB0, dB1, wB0, wB1);    __builtin_amdgcn_sched_barrier(0);
;           SW_MF(3, dB0, dB1, wB0, wB1); __builtin_amdgcn_sched_barrier(0);
;           SW_VA(dA0, dA1, wA0, wA1);    __builtin_amdgcn_sched_barrier(0);
;           SW_VA(dB0, dB1, wB0, wB1); }
.Lstag_m6:
.Lm6_loop:
	.p2align 3
	v_mfma_f32_32x32x16_bf16 v[16:31], v[132:135], v[0:3], 0
	v_mfma_f32_32x32x16_bf16 v[16:31], v[128:131], v[4:7], v[16:31]
	ds_read_b128 v[0:3], v165 offset:128
	ds_read_b128 v[4:7], v165 offset:160
	.p2align 3
	v_mfma_f32_32x32x16_bf16 v[32:47], v[132:135], v[8:11], 0
	v_mfma_f32_32x32x16_bf16 v[32:47], v[128:131], v[12:15], v[32:47]
	ds_read_b128 v[8:11], v165 offset:192
	ds_read_b128 v[12:15], v165 offset:224
	s_add_i32 s1, s18, 1
	s_cmp_lt_u32 s1, s25
	s_cselect_b32 s3, s1, s18
	s_lshl_b32 vcc_lo, s3, 7
	s_and_b32 vcc_lo, vcc_lo, 0x7fffff00
	s_lshl_b32 s3, s3, 5
	s_and_b32 s3, s3, 32
	s_or_b32 s3, vcc_lo, s3
	v_mad_u64_u32 v[114:115], vcc, s3, v223, v[140:141]
	s_lshr_b32 s0, s18, 1
	s_lshl_b32 s0, s0, 2
	s_add_i32 s0, s0, s24
	s_lshl_b32 s0, s0, 6
	s_and_b32 s2, s18, 1
	s_lshl_b32 s2, s2, 5
	s_or_b32 s0, s0, s2
	v_or_b32_e32 v124, s0, v159
	global_load_dwordx4 v[64:67], v[114:115], off
	global_load_dwordx4 v[68:71], v[114:115], off offset:32
	.p2align 3
	v_pk_mul_f32 v[16:17], v[16:17], v[112:113] clamp
	v_pk_mul_f32 v[18:19], v[18:19], v[112:113] clamp
	v_pk_mul_f32 v[20:21], v[20:21], v[112:113] clamp
	v_pk_mul_f32 v[22:23], v[22:23], v[112:113] clamp
	v_pk_mul_f32 v[24:25], v[24:25], v[112:113] clamp
	v_pk_mul_f32 v[26:27], v[26:27], v[112:113] clamp
	v_pk_mul_f32 v[28:29], v[28:29], v[112:113] clamp
	v_pk_mul_f32 v[30:31], v[30:31], v[112:113] clamp
	v_pk_fma_f32 v[88:89], v[16:17], v[80:81], 0 op_sel_hi:[1,0,0]
	v_pk_fma_f32 v[90:91], v[18:19], v[80:81], 0 op_sel_hi:[1,0,0]
	v_pk_fma_f32 v[92:93], v[20:21], v[80:81], 0 op_sel_hi:[1,0,0]
	v_pk_fma_f32 v[94:95], v[22:23], v[80:81], 0 op_sel_hi:[1,0,0]
	v_pk_fma_f32 v[96:97], v[24:25], v[80:81], 0 op_sel_hi:[1,0,0]
	v_pk_fma_f32 v[98:99], v[26:27], v[80:81], 0 op_sel_hi:[1,0,0]
	v_pk_fma_f32 v[100:101], v[28:29], v[80:81], 0 op_sel_hi:[1,0,0]
	v_pk_fma_f32 v[102:103], v[30:31], v[80:81], 0 op_sel_hi:[1,0,0]
	s_waitcnt lgkmcnt(2)
	.p2align 3
	v_mfma_f32_32x32x16_bf16 v[16:31], v[132:135], v[0:3], 0
	v_mfma_f32_32x32x16_bf16 v[16:31], v[128:131], v[4:7], v[16:31]
	ds_read_b128 v[0:3], v165 offset:256
	ds_read_b128 v[4:7], v165 offset:288
	.p2align 3
	v_pk_mul_f32 v[32:33], v[32:33], v[112:113] clamp
	v_pk_mul_f32 v[34:35], v[34:35], v[112:113] clamp
	v_pk_mul_f32 v[36:37], v[36:37], v[112:113] clamp
	v_pk_mul_f32 v[38:39], v[38:39], v[112:113] clamp
	v_pk_mul_f32 v[40:41], v[40:41], v[112:113] clamp
	v_pk_mul_f32 v[42:43], v[42:43], v[112:113] clamp
	v_pk_mul_f32 v[44:45], v[44:45], v[112:113] clamp
	v_pk_mul_f32 v[46:47], v[46:47], v[112:113] clamp
	v_pk_fma_f32 v[88:89], v[32:33], v[104:105], v[88:89] op_sel_hi:[1,0,1]
	v_pk_fma_f32 v[90:91], v[34:35], v[104:105], v[90:91] op_sel_hi:[1,0,1]
	v_pk_fma_f32 v[92:93], v[36:37], v[104:105], v[92:93] op_sel_hi:[1,0,1]
	v_pk_fma_f32 v[94:95], v[38:39], v[104:105], v[94:95] op_sel_hi:[1,0,1]
	v_pk_fma_f32 v[96:97], v[40:41], v[104:105], v[96:97] op_sel_hi:[1,0,1]
	v_pk_fma_f32 v[98:99], v[42:43], v[104:105], v[98:99] op_sel_hi:[1,0,1]
	v_pk_fma_f32 v[100:101], v[44:45], v[104:105], v[100:101] op_sel_hi:[1,0,1]
	v_pk_fma_f32 v[102:103], v[46:47], v[104:105], v[102:103] op_sel_hi:[1,0,1]
	s_waitcnt lgkmcnt(2)
	.p2align 3
	v_mfma_f32_32x32x16_bf16 v[32:47], v[132:135], v[8:11], 0
	v_mfma_f32_32x32x16_bf16 v[32:47], v[128:131], v[12:15], v[32:47]
	ds_read_b128 v[8:11], v165 offset:320
	ds_read_b128 v[12:15], v165 offset:352
	.p2align 3
	v_pk_mul_f32 v[16:17], v[16:17], v[112:113] clamp
	v_pk_mul_f32 v[18:19], v[18:19], v[112:113] clamp
	v_pk_mul_f32 v[20:21], v[20:21], v[112:113] clamp
	v_pk_mul_f32 v[22:23], v[22:23], v[112:113] clamp
	v_pk_mul_f32 v[24:25], v[24:25], v[112:113] clamp
	v_pk_mul_f32 v[26:27], v[26:27], v[112:113] clamp
	v_pk_mul_f32 v[28:29], v[28:29], v[112:113] clamp
	v_pk_mul_f32 v[30:31], v[30:31], v[112:113] clamp
	v_pk_fma_f32 v[88:89], v[16:17], v[82:83], v[88:89] op_sel_hi:[1,0,1]
	v_pk_fma_f32 v[90:91], v[18:19], v[82:83], v[90:91] op_sel_hi:[1,0,1]
	v_pk_fma_f32 v[92:93], v[20:21], v[82:83], v[92:93] op_sel_hi:[1,0,1]
	v_pk_fma_f32 v[94:95], v[22:23], v[82:83], v[94:95] op_sel_hi:[1,0,1]
	v_pk_fma_f32 v[96:97], v[24:25], v[82:83], v[96:97] op_sel_hi:[1,0,1]
	v_pk_fma_f32 v[98:99], v[26:27], v[82:83], v[98:99] op_sel_hi:[1,0,1]
	v_pk_fma_f32 v[100:101], v[28:29], v[82:83], v[100:101] op_sel_hi:[1,0,1]
	v_pk_fma_f32 v[102:103], v[30:31], v[82:83], v[102:103] op_sel_hi:[1,0,1]
	s_waitcnt lgkmcnt(2)
	.p2align 3
	v_mfma_f32_32x32x16_bf16 v[16:31], v[132:135], v[0:3], 0
	v_mfma_f32_32x32x16_bf16 v[16:31], v[128:131], v[4:7], v[16:31]
	ds_read_b128 v[0:3], v165 offset:384
	ds_read_b128 v[4:7], v165 offset:416
	.p2align 3
	v_pk_mul_f32 v[32:33], v[32:33], v[112:113] clamp
	v_pk_mul_f32 v[34:35], v[34:35], v[112:113] clamp
	v_pk_mul_f32 v[36:37], v[36:37], v[112:113] clamp
	v_pk_mul_f32 v[38:39], v[38:39], v[112:113] clamp
	v_pk_mul_f32 v[40:41], v[40:41], v[112:113] clamp
	v_pk_mul_f32 v[42:43], v[42:43], v[112:113] clamp
	v_pk_mul_f32 v[44:45], v[44:45], v[112:113] clamp
	v_pk_mul_f32 v[46:47], v[46:47], v[112:113] clamp
	v_pk_fma_f32 v[88:89], v[32:33], v[106:107], v[88:89] op_sel_hi:[1,0,1]
	v_pk_fma_f32 v[90:91], v[34:35], v[106:107], v[90:91] op_sel_hi:[1,0,1]
	v_pk_fma_f32 v[92:93], v[36:37], v[106:107], v[92:93] op_sel_hi:[1,0,1]
	v_pk_fma_f32 v[94:95], v[38:39], v[106:107], v[94:95] op_sel_hi:[1,0,1]
	v_pk_fma_f32 v[96:97], v[40:41], v[106:107], v[96:97] op_sel_hi:[1,0,1]
	v_pk_fma_f32 v[98:99], v[42:43], v[106:107], v[98:99] op_sel_hi:[1,0,1]
	v_pk_fma_f32 v[100:101], v[44:45], v[106:107], v[100:101] op_sel_hi:[1,0,1]
	v_pk_fma_f32 v[102:103], v[46:47], v[106:107], v[102:103] op_sel_hi:[1,0,1]
	s_waitcnt lgkmcnt(2)
; __device__ __forceinline__ unsigned sortable(float f) { const unsigned u = __float_as_uint(f); return u ^ ((unsigned)((int)u >> 31) | 0x80000000u); }
; __device__ __forceinline__ int bucketf(float f) { const unsigned u = __float_as_uint(f); const int idx = (int)((u >> 20) & 0x7FFu); const int c = min(max(idx - 816, 128), 255); return c ^ (((int)u >> 31) & 255); }
;     ...
;         { f32x16 zero16;
; #pragma unroll
;           for (int r = 0; r < 16; ++r) zero16[r] = 0.f;
;           f32x16 dA0, dA1, dB0, dB1; float wA0, wA1, wB0, wB1;
;           SW_MF(0, dA0, dA1, wA0, wA1);
;           SW_MF(1, dB0, dB1, wB0, wB1); __builtin_amdgcn_sched_barrier(0);
;           SW_VA(dA0, dA1, wA0, wA1);    __builtin_amdgcn_sched_barrier(0);
;           SW_MF(2, dA0, dA1, wA0, wA1); __builtin_amdgcn_sched_barrier(0);
;           SW_VA(dB0, dB1, wB0, wB1);    __builtin_amdgcn_sched_barrier(0);
;           SW_MF(3, dB0, dB1, wB0, wB1); __builtin_amdgcn_sched_barrier(0);
;           SW_VA(dA0, dA1, wA0, wA1);    __builtin_amdgcn_sched_barrier(0);
;           SW_VA(dB0, dB1, wB0, wB1); }
;     ...
;         f32x16 sc;
; #pragma unroll
;         for (int r = 0; r < 16; ++r) sc[r] = sc2[r >> 1][r & 1];
;         const unsigned s0 = (unsigned)(64 * kt + 32 * kb + 4 * hi);
; #pragma unroll
;         for (int r = 0; r < 16; ++r) { const unsigned s = s0 + (unsigned)((r & 3) + 8 * (r >> 2));
;             if (MODE == 5) { __hip_atomic_fetch_add(hist + 64 * bucketf(sc[r]), 1u, __ATOMIC_RELAXED, __HIP_MEMORY_SCOPE_WORKGROUP); continue; }
;             if (MODE == 6) {
;                 if (sc[r] >= t_hi) { const unsigned pos = __hip_atomic_fetch_add(cnt, 1u, __ATOMIC_RELAXED, __HIP_MEMORY_SCOPE_WORKGROUP); sel[pos & 255u] = (unsigned short)s; }
;                 else if (sc[r] >= t_lo) { const unsigned key = (sortable(sc[r]) & 0xFFFFE000u) | (8191u - s);
;                     const unsigned pos = __hip_atomic_fetch_add(ccnt, 1u, __ATOMIC_RELAXED, __HIP_MEMORY_SCOPE_WORKGROUP); cand[pos & (DS_CAP - 1)] = key; }
	.p2align 3
	v_mfma_f32_32x32x16_bf16 v[32:47], v[132:135], v[8:11], 0
	v_mfma_f32_32x32x16_bf16 v[32:47], v[128:131], v[12:15], v[32:47]
	ds_read_b128 v[8:11], v165 offset:448
	ds_read_b128 v[12:15], v165 offset:480
	.p2align 3
	v_pk_mul_f32 v[16:17], v[16:17], v[112:113] clamp
	v_pk_mul_f32 v[18:19], v[18:19], v[112:113] clamp
	v_pk_mul_f32 v[20:21], v[20:21], v[112:113] clamp
	v_pk_mul_f32 v[22:23], v[22:23], v[112:113] clamp
	v_pk_mul_f32 v[24:25], v[24:25], v[112:113] clamp
	v_pk_mul_f32 v[26:27], v[26:27], v[112:113] clamp
	v_pk_mul_f32 v[28:29], v[28:29], v[112:113] clamp
	v_pk_mul_f32 v[30:31], v[30:31], v[112:113] clamp
	v_pk_fma_f32 v[88:89], v[16:17], v[84:85], v[88:89] op_sel_hi:[1,0,1]
	v_pk_fma_f32 v[90:91], v[18:19], v[84:85], v[90:91] op_sel_hi:[1,0,1]
	v_pk_fma_f32 v[92:93], v[20:21], v[84:85], v[92:93] op_sel_hi:[1,0,1]
	v_pk_fma_f32 v[94:95], v[22:23], v[84:85], v[94:95] op_sel_hi:[1,0,1]
	v_pk_fma_f32 v[96:97], v[24:25], v[84:85], v[96:97] op_sel_hi:[1,0,1]
	v_pk_fma_f32 v[98:99], v[26:27], v[84:85], v[98:99] op_sel_hi:[1,0,1]
	v_pk_fma_f32 v[100:101], v[28:29], v[84:85], v[100:101] op_sel_hi:[1,0,1]
	v_pk_fma_f32 v[102:103], v[30:31], v[84:85], v[102:103] op_sel_hi:[1,0,1]
	s_waitcnt lgkmcnt(2)
	.p2align 3
	v_mfma_f32_32x32x16_bf16 v[16:31], v[132:135], v[0:3], 0
	v_mfma_f32_32x32x16_bf16 v[16:31], v[128:131], v[4:7], v[16:31]
	ds_read_b128 v[0:3], v165
	ds_read_b128 v[4:7], v165 offset:32
	.p2align 3
	v_pk_mul_f32 v[32:33], v[32:33], v[112:113] clamp
	v_pk_mul_f32 v[34:35], v[34:35], v[112:113] clamp
	v_pk_mul_f32 v[36:37], v[36:37], v[112:113] clamp
	v_pk_mul_f32 v[38:39], v[38:39], v[112:113] clamp
	v_pk_mul_f32 v[40:41], v[40:41], v[112:113] clamp
	v_pk_mul_f32 v[42:43], v[42:43], v[112:113] clamp
	v_pk_mul_f32 v[44:45], v[44:45], v[112:113] clamp
	v_pk_mul_f32 v[46:47], v[46:47], v[112:113] clamp
	v_pk_fma_f32 v[88:89], v[32:33], v[108:109], v[88:89] op_sel_hi:[1,0,1]
	v_pk_fma_f32 v[90:91], v[34:35], v[108:109], v[90:91] op_sel_hi:[1,0,1]
	v_pk_fma_f32 v[92:93], v[36:37], v[108:109], v[92:93] op_sel_hi:[1,0,1]
	v_pk_fma_f32 v[94:95], v[38:39], v[108:109], v[94:95] op_sel_hi:[1,0,1]
	v_pk_fma_f32 v[96:97], v[40:41], v[108:109], v[96:97] op_sel_hi:[1,0,1]
	v_pk_fma_f32 v[98:99], v[42:43], v[108:109], v[98:99] op_sel_hi:[1,0,1]
	v_pk_fma_f32 v[100:101], v[44:45], v[108:109], v[100:101] op_sel_hi:[1,0,1]
	v_pk_fma_f32 v[102:103], v[46:47], v[108:109], v[102:103] op_sel_hi:[1,0,1]
	s_waitcnt lgkmcnt(2)
	.p2align 3
	v_mfma_f32_32x32x16_bf16 v[32:47], v[132:135], v[8:11], 0
	v_mfma_f32_32x32x16_bf16 v[32:47], v[128:131], v[12:15], v[32:47]
	ds_read_b128 v[8:11], v165 offset:64
	ds_read_b128 v[12:15], v165 offset:96
	.p2align 3
	v_pk_mul_f32 v[16:17], v[16:17], v[112:113] clamp
	v_pk_mul_f32 v[18:19], v[18:19], v[112:113] clamp
	v_pk_mul_f32 v[20:21], v[20:21], v[112:113] clamp
	v_pk_mul_f32 v[22:23], v[22:23], v[112:113] clamp
	v_pk_mul_f32 v[24:25], v[24:25], v[112:113] clamp
	v_pk_mul_f32 v[26:27], v[26:27], v[112:113] clamp
	v_pk_mul_f32 v[28:29], v[28:29], v[112:113] clamp
	v_pk_mul_f32 v[30:31], v[30:31], v[112:113] clamp
	v_pk_fma_f32 v[88:89], v[16:17], v[86:87], v[88:89] op_sel_hi:[1,0,1]
	v_pk_fma_f32 v[90:91], v[18:19], v[86:87], v[90:91] op_sel_hi:[1,0,1]
	v_pk_fma_f32 v[92:93], v[20:21], v[86:87], v[92:93] op_sel_hi:[1,0,1]
	v_pk_fma_f32 v[94:95], v[22:23], v[86:87], v[94:95] op_sel_hi:[1,0,1]
	v_pk_fma_f32 v[96:97], v[24:25], v[86:87], v[96:97] op_sel_hi:[1,0,1]
	v_pk_fma_f32 v[98:99], v[26:27], v[86:87], v[98:99] op_sel_hi:[1,0,1]
	v_pk_fma_f32 v[100:101], v[28:29], v[86:87], v[100:101] op_sel_hi:[1,0,1]
	v_pk_fma_f32 v[102:103], v[30:31], v[86:87], v[102:103] op_sel_hi:[1,0,1]
	.p2align 3
	v_pk_mul_f32 v[32:33], v[32:33], v[112:113] clamp
	v_pk_mul_f32 v[34:35], v[34:35], v[112:113] clamp
	v_pk_mul_f32 v[36:37], v[36:37], v[112:113] clamp
	v_pk_mul_f32 v[38:39], v[38:39], v[112:113] clamp
	v_pk_mul_f32 v[40:41], v[40:41], v[112:113] clamp
	v_pk_mul_f32 v[42:43], v[42:43], v[112:113] clamp
	v_pk_mul_f32 v[44:45], v[44:45], v[112:113] clamp
	v_pk_mul_f32 v[46:47], v[46:47], v[112:113] clamp
	v_pk_fma_f32 v[88:89], v[32:33], v[110:111], v[88:89] op_sel_hi:[1,0,1]
	v_pk_fma_f32 v[90:91], v[34:35], v[110:111], v[90:91] op_sel_hi:[1,0,1]
	v_pk_fma_f32 v[92:93], v[36:37], v[110:111], v[92:93] op_sel_hi:[1,0,1]
	v_pk_fma_f32 v[94:95], v[38:39], v[110:111], v[94:95] op_sel_hi:[1,0,1]
	v_pk_fma_f32 v[96:97], v[40:41], v[110:111], v[96:97] op_sel_hi:[1,0,1]
	v_pk_fma_f32 v[98:99], v[42:43], v[110:111], v[98:99] op_sel_hi:[1,0,1]
	v_pk_fma_f32 v[100:101], v[44:45], v[110:111], v[100:101] op_sel_hi:[1,0,1]
	v_pk_fma_f32 v[102:103], v[46:47], v[110:111], v[102:103] op_sel_hi:[1,0,1]
	s_waitcnt lgkmcnt(0)
	v_cmp_ge_f32_e64 s[40:41], v88, v122
	v_cmp_ge_f32_e64 s[42:43], v88, v123
	v_mov_b32_e32 v18, v124
	v_cndmask_b32_e64 v56, v171, v180, s[40:41]
	s_mov_b64 exec, s[42:43]
	ds_add_rtn_u32 v16, v56, v222
	s_andn2_b64 s[42:43], s[42:43], s[40:41]
	s_mov_b64 exec, -1
	v_cmp_ge_f32_e64 s[44:45], v89, v122
	v_cmp_ge_f32_e64 s[22:23], v89, v123
	v_or_b32_e32 v19, 1, v124
	v_cndmask_b32_e64 v57, v171, v180, s[44:45]
	s_mov_b64 exec, s[22:23]
	ds_add_rtn_u32 v17, v57, v222
	s_andn2_b64 s[22:23], s[22:23], s[44:45]
	s_mov_b64 exec, -1
	v_cmp_ge_f32_e64 s[20:21], v90, v122
	v_cmp_ge_f32_e64 s[2:3], v90, v123
	v_or_b32_e32 v24, 2, v124
	v_cndmask_b32_e64 v58, v171, v180, s[20:21]
	s_mov_b64 exec, s[2:3]
	ds_add_rtn_u32 v23, v58, v222
	s_andn2_b64 s[2:3], s[2:3], s[20:21]
	s_mov_b64 exec, -1
	s_waitcnt lgkmcnt(2)
	v_and_b32_e32 v16, 0xff, v16
	s_mov_b64 exec, s[40:41]
	v_lshl_add_u32 v20, v16, 1, v179
	ds_write_b16 v20, v18
	s_mov_b64 exec, s[42:43]
	s_cbranch_execz .Lm6_nb0
	v_ashrrev_i32_e32 v22, 31, v88
	v_sub_u32_e32 v18, 0x1fff, v18
	v_lshl_add_u32 v20, v16, 2, v169
	v_bitop3_b32 v21, v22, v88, s64 bitop3:0x36
	v_and_or_b32 v21, v21, s65, v18
	ds_write_b32 v20, v21

;     ...
;         a0 = n0; a1 = n1;
;     }
.Lm6_nb15:
	s_mov_b64 exec, -1
	s_waitcnt vmcnt(0)
	v_mov_b64_e32 v[132:133], v[64:65]
	v_mov_b64_e32 v[134:135], v[66:67]
	v_mov_b64_e32 v[128:129], v[68:69]
	v_mov_b64_e32 v[130:131], v[70:71]
	s_cmp_lg_u32 s25, s1
	s_mov_b32 s18, s1
	s_cbranch_scc1 .Lm6_loop
	s_nop 0
.LBB0_1620:
	s_mov_b64 s[0:1], 0
